# in-projection: the epilogue's 256 row sums of squares are staged into spare LDS by LDS-DMA at the start of the tile (no global loads in the epilogue)
# baseline (speedup 1.0000x reference)
;     __device__ __forceinline__ void operator()(const f32x4 (&acc)[2][2][4][2], const Unit& u, int wr, int wc, int fr, int fq) const {
;         const int row0 = u.pm * BM + wr * 64 + fr; const bool second = split > 0 && u.pn >= split; const int col0 = (second ? u.pn - split : u.pn) * BM + wc * 32 + 8 * fq;
;         bf16_t* const Ob = second ? O2 : O; const int ld = second ? ldc2 : ldc;
; #pragma unroll
;         for (int ai = 0; ai < 2; ++ai)
; #pragma unroll
;             for (int m = 0; m < 4; ++m) { bf16_t* rowp = Ob + (size_t)(row0 + ai * HALF + m * 16) * ld + col0;
;                 float rs = 1.f; if (ss) rs = __builtin_amdgcn_rsqf((float)ss[row0 + ai * HALF + m * 16] * (1.f / (2048.f * 262144.f)) + 1e-6f);
; template <class Epi, class Sched, bool ALIGN_EPI = false, bool SP2 = false>
; __device__ __forceinline__ void gemm_phase(PG8_LAS unsigned char* lds, const Gemm g, const Sched& S, const Epi& E) {
;     ...
;     for (;;) {
;         const bool has_next = S.next(ui + 1, nxt);
;         const char* nA = has_next ? (const char*)g.A + (size_t)nxt.pm * tstep : cA; const char* nB = has_next ? (const char*)g.Bt + (size_t)nxt.pn * tstep : cB;
;         for (int t = 0; t < nt; t += 2) {
;             const bool last = (t == nt - 2);
;             const char* a1 = cA + (size_t)(t + 1) * kstep;
;             const char* a2 = last ? nA : cA + (size_t)(t + 2) * kstep; const char* b2 = last ? nB : cB + (size_t)(t + 2) * kstep;
;             const char* a3 = a2 + kstep; const char* b3 = b2 + kstep;
;             if (last && has_next) S.a_ready(nxt);
.LBB0_558:
	v_readfirstlane_b32 s98, v227
	s_lshr_b32 s98, s98, 6
	s_cmp_gt_u32 s98, 1
	s_cbranch_scc1 .Lstg4_done
	s_and_b32 s99, s55, 1
	s_lshl_b32 s99, s99, 12
	s_add_i32 s99, s99, 0x20000
	s_lshl_b32 s100, s98, 10
	s_add_i32 s99, s99, s100
	v_and_b32_e32 v246, 63, v227
	v_mov_b32_e32 v245, 0
	s_lshl_b32 s100, s42, 8
	s_lshl_b32 s101, s98, 7
	s_add_i32 s100, s100, s101
	s_lshl_b32 s100, s100, 3
	v_lshl_add_u32 v244, v246, 4, s100
	s_nop 0
	v_lshl_add_u64 v[244:245], v[244:245], 0, s[12:13]
	s_mov_b32 m0, s99
	s_nop 0
	global_load_lds_dwordx4 v[244:245], off

; __device__ __forceinline__ unsigned cvt_pk_bf16(float lo, float hi) { unsigned r; asm volatile("v_cvt_pk_bf16_f32 %0, %1, %2" : "=v"(r) : "v"(lo), "v"(hi)); return r; }
;     __device__ __forceinline__ void operator()(const f32x4 (&acc)[2][2][4][2], const Unit& u, int wr, int wc, int fr, int fq) const {
;         const int row0 = u.pm * BM + wr * 64 + fr; const bool second = split > 0 && u.pn >= split; const int col0 = (second ? u.pn - split : u.pn) * BM + wc * 32 + 8 * fq;
;         bf16_t* const Ob = second ? O2 : O; const int ld = second ? ldc2 : ldc;
; #pragma unroll
;         for (int ai = 0; ai < 2; ++ai)
; #pragma unroll
;             for (int m = 0; m < 4; ++m) { bf16_t* rowp = Ob + (size_t)(row0 + ai * HALF + m * 16) * ld + col0;
;                 float rs = 1.f; if (ss) rs = __builtin_amdgcn_rsqf((float)ss[row0 + ai * HALF + m * 16] * (1.f / (2048.f * 262144.f)) + 1e-6f);
; #pragma unroll
;                 for (int bj = 0; bj < 2; ++bj) { const f32x4 v0 = acc[ai][bj][m][0] * rs, v1 = acc[ai][bj][m][1] * rs;
;                     u32x4 w; w.x = cvt_pk_bf16(v0[0], v0[1]); w.y = cvt_pk_bf16(v0[2], v0[3]); w.z = cvt_pk_bf16(v1[0], v1[1]); w.w = cvt_pk_bf16(v1[2], v1[3]);
;                     *(u32x4*)(rowp + bj * HALF) = w; } }
.LBB0_562:
	v_lshl_add_u32 v140, s42, 8, v147
	v_ashrrev_i32_e32 v141, 31, v140
	v_cndmask_b32_e64 v142, 0, 1, s[20:21]
	v_mov_b32_e32 v146, 1.0
	v_cmp_ne_u32_e64 s[42:43], 1, v142
	s_andn2_b64 vcc, exec, s[20:21]
	s_and_b32 s98, s55, 1
	s_lshl_b32 s98, s98, 12
	s_add_i32 s98, s98, 0x20000
	v_lshl_add_u32 v142, v147, 3, s98
	v_mov_b32_e32 v148, 1.0
	s_cbranch_vccnz .LBB0_564
	ds_read_b64 v[160:161], v142
	ds_read_b64 v[162:163], v142 offset:128
	ds_read_b64 v[164:165], v142 offset:256
	ds_read_b64 v[166:167], v142 offset:384
	ds_read_b64 v[168:169], v142 offset:1024
	ds_read_b64 v[170:171], v142 offset:1152
	ds_read_b64 v[172:173], v142 offset:1280
	ds_read_b64 v[174:175], v142 offset:1408
	s_waitcnt lgkmcnt(0)
	v_mov_b32_e32 v144, v160
	v_mov_b32_e32 v145, v161
	v_ffbh_u32_e32 v141, v145
	v_min_u32_e32 v141, 32, v141
	v_lshlrev_b64 v[144:145], v141, v[144:145]
	v_min_u32_e32 v144, 1, v144
	v_or_b32_e32 v144, v145, v144
	v_cvt_f32_u32_e32 v144, v144
	v_sub_u32_e32 v141, 32, v141
	v_ldexp_f32 v141, v144, v141
	v_fmamk_f32 v141, v141, 0x31000000, v232
	v_rsq_f32_e32 v148, v141
.LBB0_564:
	s_cmp_gt_i32 s16, 8
	s_cselect_b32 s11, -9, 0
	s_movk_i32 s10, 0x900
	s_cselect_b32 s23, s81, s2
	s_cselect_b32 s37, s80, s1
	s_cselect_b32 s10, 0x1080, s10
	s_add_i32 s11, s11, s16
	v_lshl_or_b32 v144, s11, 8, v150
	v_mov_b32_e32 v152, s37
	v_mov_b32_e32 v153, s23
	v_ashrrev_i32_e32 v145, 31, v144
	v_lshl_add_u64 v[144:145], v[144:145], 1, v[152:153]
	v_mad_i64_i32 v[152:153], s[50:51], s10, v140, 0
	v_lshl_add_u64 v[152:153], v[152:153], 1, v[144:145]
	v_pk_mul_f32 v[128:129], v[128:129], v[148:149] op_sel_hi:[1,0]
	v_pk_mul_f32 v[126:127], v[126:127], v[148:149] op_sel_hi:[1,0]
	v_pk_mul_f32 v[154:155], v[124:125], v[148:149] op_sel_hi:[1,0]
	v_pk_mul_f32 v[124:125], v[122:123], v[148:149] op_sel_hi:[1,0]
	v_cvt_pk_bf16_f32 v122, v126, v127
	v_cvt_pk_bf16_f32 v123, v128, v129
	s_and_b64 vcc, exec, s[42:43]
	v_cvt_pk_bf16_f32 v124, v124, v125
	v_cvt_pk_bf16_f32 v125, v154, v155
	global_store_dwordx4 v[152:153], v[122:125], off
	v_pk_mul_f32 v[120:121], v[120:121], v[148:149] op_sel_hi:[1,0]
	v_pk_mul_f32 v[118:119], v[118:119], v[148:149] op_sel_hi:[1,0]
	v_pk_mul_f32 v[122:123], v[116:117], v[148:149] op_sel_hi:[1,0]
	v_pk_mul_f32 v[116:117], v[114:115], v[148:149] op_sel_hi:[1,0]
	v_cvt_pk_bf16_f32 v114, v118, v119
	v_cvt_pk_bf16_f32 v115, v120, v121
	s_nop 0
	v_cvt_pk_bf16_f32 v116, v116, v117
	v_cvt_pk_bf16_f32 v117, v122, v123
	global_store_dwordx4 v[152:153], v[114:117], off offset:256
	s_cbranch_vccnz .LBB0_566
	s_nop 0
	v_mov_b32_e32 v114, v162
	v_mov_b32_e32 v115, v163
	v_ffbh_u32_e32 v116, v115
	v_min_u32_e32 v116, 32, v116
	v_lshlrev_b64 v[114:115], v116, v[114:115]
	v_min_u32_e32 v114, 1, v114
	v_or_b32_e32 v114, v115, v114
	v_cvt_f32_u32_e32 v114, v114
	v_sub_u32_e32 v115, 32, v116
	v_ldexp_f32 v114, v114, v115
	v_fmamk_f32 v114, v114, 0x31000000, v232
	v_rsq_f32_e32 v146, v114
.LBB0_566:
	s_nop 0
	v_or_b32_e32 v114, 16, v140
	v_mad_i64_i32 v[114:115], s[50:51], s10, v114, 0
	v_lshl_add_u64 v[114:115], v[114:115], 1, v[144:145]
	v_pk_mul_f32 v[112:113], v[112:113], v[146:147] op_sel_hi:[1,0]
	v_pk_mul_f32 v[110:111], v[110:111], v[146:147] op_sel_hi:[1,0]
	v_pk_mul_f32 v[116:117], v[108:109], v[146:147] op_sel_hi:[1,0]
	v_pk_mul_f32 v[108:109], v[106:107], v[146:147] op_sel_hi:[1,0]
	v_cvt_pk_bf16_f32 v106, v110, v111
	v_cvt_pk_bf16_f32 v107, v112, v113
	v_pk_mul_f32 v[104:105], v[104:105], v[146:147] op_sel_hi:[1,0]
	v_cvt_pk_bf16_f32 v108, v108, v109
	v_cvt_pk_bf16_f32 v109, v116, v117
	global_store_dwordx4 v[114:115], v[106:109], off
	v_pk_mul_f32 v[102:103], v[102:103], v[146:147] op_sel_hi:[1,0]
	s_and_b64 vcc, exec, s[42:43]
	v_pk_mul_f32 v[106:107], v[100:101], v[146:147] op_sel_hi:[1,0]
	v_pk_mul_f32 v[100:101], v[98:99], v[146:147] op_sel_hi:[1,0]
	v_cvt_pk_bf16_f32 v98, v102, v103
	v_cvt_pk_bf16_f32 v99, v104, v105
	s_nop 0
	v_cvt_pk_bf16_f32 v100, v100, v101
	v_cvt_pk_bf16_f32 v101, v106, v107
	global_store_dwordx4 v[114:115], v[98:101], off offset:256
	s_nop 1
	v_mov_b32_e32 v98, 1.0
	v_mov_b32_e32 v100, 1.0
	s_cbranch_vccnz .LBB0_568
	s_nop 0
	v_mov_b32_e32 v100, v164
	v_mov_b32_e32 v101, v165
	v_ffbh_u32_e32 v99, v101
	v_min_u32_e32 v99, 32, v99
	v_lshlrev_b64 v[100:101], v99, v[100:101]
	v_min_u32_e32 v100, 1, v100
	v_or_b32_e32 v100, v101, v100
	v_cvt_f32_u32_e32 v100, v100
	v_sub_u32_e32 v99, 32, v99
	v_ldexp_f32 v99, v100, v99
	v_fmamk_f32 v99, v99, 0x31000000, v232
	v_rsq_f32_e32 v100, v99
.LBB0_568:
	v_or_b32_e32 v99, 32, v140
	v_mad_i64_i32 v[102:103], s[50:51], s10, v99, 0
	v_lshl_add_u64 v[102:103], v[102:103], 1, v[144:145]
	v_pk_mul_f32 v[96:97], v[96:97], v[100:101] op_sel_hi:[1,0]
	v_pk_mul_f32 v[94:95], v[94:95], v[100:101] op_sel_hi:[1,0]
	v_pk_mul_f32 v[104:105], v[92:93], v[100:101] op_sel_hi:[1,0]
	v_pk_mul_f32 v[92:93], v[90:91], v[100:101] op_sel_hi:[1,0]
	v_cvt_pk_bf16_f32 v90, v94, v95
	v_cvt_pk_bf16_f32 v91, v96, v97
	s_and_b64 vcc, exec, s[42:43]
	v_cvt_pk_bf16_f32 v92, v92, v93
	v_cvt_pk_bf16_f32 v93, v104, v105
	global_store_dwordx4 v[102:103], v[90:93], off
	v_pk_mul_f32 v[88:89], v[88:89], v[100:101] op_sel_hi:[1,0]
	v_pk_mul_f32 v[86:87], v[86:87], v[100:101] op_sel_hi:[1,0]
	v_pk_mul_f32 v[90:91], v[84:85], v[100:101] op_sel_hi:[1,0]
	v_pk_mul_f32 v[84:85], v[82:83], v[100:101] op_sel_hi:[1,0]
	v_cvt_pk_bf16_f32 v82, v86, v87
	v_cvt_pk_bf16_f32 v83, v88, v89
	s_nop 0
	v_cvt_pk_bf16_f32 v84, v84, v85
	v_cvt_pk_bf16_f32 v85, v90, v91
	global_store_dwordx4 v[102:103], v[82:85], off offset:256
	s_cbranch_vccnz .LBB0_570
	s_nop 0
	v_mov_b32_e32 v82, v166
	v_mov_b32_e32 v83, v167
	v_ffbh_u32_e32 v84, v83
	v_min_u32_e32 v84, 32, v84
	v_lshlrev_b64 v[82:83], v84, v[82:83]
	v_min_u32_e32 v82, 1, v82
	v_or_b32_e32 v82, v83, v82
	v_cvt_f32_u32_e32 v82, v82
	v_sub_u32_e32 v83, 32, v84
	v_ldexp_f32 v82, v82, v83
	v_fmamk_f32 v82, v82, 0x31000000, v232
	v_rsq_f32_e32 v98, v82
; __device__ __forceinline__ unsigned cvt_pk_bf16(float lo, float hi) { unsigned r; asm volatile("v_cvt_pk_bf16_f32 %0, %1, %2" : "=v"(r) : "v"(lo), "v"(hi)); return r; }
;     __device__ __forceinline__ void operator()(const f32x4 (&acc)[2][2][4][2], const Unit& u, int wr, int wc, int fr, int fq) const {
;     ...
;             for (int m = 0; m < 4; ++m) { bf16_t* rowp = Ob + (size_t)(row0 + ai * HALF + m * 16) * ld + col0;
;                 float rs = 1.f; if (ss) rs = __builtin_amdgcn_rsqf((float)ss[row0 + ai * HALF + m * 16] * (1.f / (2048.f * 262144.f)) + 1e-6f);
; #pragma unroll
;                 for (int bj = 0; bj < 2; ++bj) { const f32x4 v0 = acc[ai][bj][m][0] * rs, v1 = acc[ai][bj][m][1] * rs;
;                     u32x4 w; w.x = cvt_pk_bf16(v0[0], v0[1]); w.y = cvt_pk_bf16(v0[2], v0[3]); w.z = cvt_pk_bf16(v1[0], v1[1]); w.w = cvt_pk_bf16(v1[2], v1[3]);
;                     *(u32x4*)(rowp + bj * HALF) = w; } }
.LBB0_570:
	s_nop 0
	v_or_b32_e32 v82, 48, v140
	v_mad_i64_i32 v[82:83], s[50:51], s10, v82, 0
	v_lshl_add_u64 v[82:83], v[82:83], 1, v[144:145]
	v_pk_mul_f32 v[80:81], v[80:81], v[98:99] op_sel_hi:[1,0]
	v_pk_mul_f32 v[78:79], v[78:79], v[98:99] op_sel_hi:[1,0]
	v_pk_mul_f32 v[84:85], v[76:77], v[98:99] op_sel_hi:[1,0]
	v_pk_mul_f32 v[76:77], v[74:75], v[98:99] op_sel_hi:[1,0]
	v_cvt_pk_bf16_f32 v74, v78, v79
	v_cvt_pk_bf16_f32 v75, v80, v81
	v_pk_mul_f32 v[72:73], v[72:73], v[98:99] op_sel_hi:[1,0]
	v_cvt_pk_bf16_f32 v76, v76, v77
	v_cvt_pk_bf16_f32 v77, v84, v85
	global_store_dwordx4 v[82:83], v[74:77], off
	v_pk_mul_f32 v[70:71], v[70:71], v[98:99] op_sel_hi:[1,0]
	s_and_b64 vcc, exec, s[42:43]
	v_pk_mul_f32 v[74:75], v[68:69], v[98:99] op_sel_hi:[1,0]
	v_pk_mul_f32 v[68:69], v[66:67], v[98:99] op_sel_hi:[1,0]
	v_cvt_pk_bf16_f32 v66, v70, v71
	v_cvt_pk_bf16_f32 v67, v72, v73
	s_nop 0
	v_cvt_pk_bf16_f32 v68, v68, v69
	v_cvt_pk_bf16_f32 v69, v74, v75
	global_store_dwordx4 v[82:83], v[66:69], off offset:256
	s_nop 1
	v_mov_b32_e32 v66, 1.0
	v_mov_b32_e32 v68, 1.0
	s_cbranch_vccnz .LBB0_572
	s_nop 0
	v_mov_b32_e32 v68, v168
	v_mov_b32_e32 v69, v169
	v_ffbh_u32_e32 v67, v69
	v_min_u32_e32 v67, 32, v67
	v_lshlrev_b64 v[68:69], v67, v[68:69]
	v_min_u32_e32 v68, 1, v68
	v_or_b32_e32 v68, v69, v68
	v_cvt_f32_u32_e32 v68, v68
	v_sub_u32_e32 v67, 32, v67
	v_ldexp_f32 v67, v68, v67
	v_fmamk_f32 v67, v67, 0x31000000, v232
	v_rsq_f32_e32 v68, v67
.LBB0_572:
	v_add_u32_e32 v67, 0x80, v140
	v_mad_i64_i32 v[70:71], s[50:51], s10, v67, 0
	v_lshl_add_u64 v[70:71], v[70:71], 1, v[144:145]
	v_pk_mul_f32 v[64:65], v[64:65], v[68:69] op_sel_hi:[1,0]
	v_pk_mul_f32 v[62:63], v[62:63], v[68:69] op_sel_hi:[1,0]
	v_pk_mul_f32 v[72:73], v[60:61], v[68:69] op_sel_hi:[1,0]
	v_pk_mul_f32 v[60:61], v[58:59], v[68:69] op_sel_hi:[1,0]
	v_cvt_pk_bf16_f32 v58, v62, v63
	v_cvt_pk_bf16_f32 v59, v64, v65
	s_and_b64 vcc, exec, s[42:43]
	v_cvt_pk_bf16_f32 v60, v60, v61
	v_cvt_pk_bf16_f32 v61, v72, v73
	global_store_dwordx4 v[70:71], v[58:61], off
	v_pk_mul_f32 v[56:57], v[56:57], v[68:69] op_sel_hi:[1,0]
	v_pk_mul_f32 v[54:55], v[54:55], v[68:69] op_sel_hi:[1,0]
	v_pk_mul_f32 v[58:59], v[52:53], v[68:69] op_sel_hi:[1,0]
	v_pk_mul_f32 v[52:53], v[50:51], v[68:69] op_sel_hi:[1,0]
	v_cvt_pk_bf16_f32 v50, v54, v55
	v_cvt_pk_bf16_f32 v51, v56, v57
	s_nop 0
	v_cvt_pk_bf16_f32 v52, v52, v53
	v_cvt_pk_bf16_f32 v53, v58, v59
	global_store_dwordx4 v[70:71], v[50:53], off offset:256
	s_cbranch_vccnz .LBB0_574
	s_nop 0
	v_mov_b32_e32 v50, v170
	v_mov_b32_e32 v51, v171
	v_ffbh_u32_e32 v52, v51
	v_min_u32_e32 v52, 32, v52
	v_lshlrev_b64 v[50:51], v52, v[50:51]
	v_min_u32_e32 v50, 1, v50
	v_or_b32_e32 v50, v51, v50
	v_cvt_f32_u32_e32 v50, v50
	v_sub_u32_e32 v51, 32, v52
	v_ldexp_f32 v50, v50, v51
	v_fmamk_f32 v50, v50, 0x31000000, v232
	v_rsq_f32_e32 v66, v50
.LBB0_574:
	s_nop 0
	v_add_u32_e32 v50, 0x90, v140
	v_mad_i64_i32 v[50:51], s[50:51], s10, v50, 0
	v_lshl_add_u64 v[50:51], v[50:51], 1, v[144:145]
	v_pk_mul_f32 v[48:49], v[48:49], v[66:67] op_sel_hi:[1,0]
	v_pk_mul_f32 v[46:47], v[46:47], v[66:67] op_sel_hi:[1,0]
	v_pk_mul_f32 v[52:53], v[44:45], v[66:67] op_sel_hi:[1,0]
	v_pk_mul_f32 v[44:45], v[42:43], v[66:67] op_sel_hi:[1,0]
	v_cvt_pk_bf16_f32 v42, v46, v47
	v_cvt_pk_bf16_f32 v43, v48, v49
	v_pk_mul_f32 v[40:41], v[40:41], v[66:67] op_sel_hi:[1,0]
	v_cvt_pk_bf16_f32 v44, v44, v45
	v_cvt_pk_bf16_f32 v45, v52, v53
	global_store_dwordx4 v[50:51], v[42:45], off
	v_pk_mul_f32 v[38:39], v[38:39], v[66:67] op_sel_hi:[1,0]
	s_and_b64 vcc, exec, s[42:43]
	v_pk_mul_f32 v[42:43], v[36:37], v[66:67] op_sel_hi:[1,0]
	v_pk_mul_f32 v[36:37], v[34:35], v[66:67] op_sel_hi:[1,0]
	v_cvt_pk_bf16_f32 v34, v38, v39
	v_cvt_pk_bf16_f32 v35, v40, v41
	s_nop 0
	v_cvt_pk_bf16_f32 v36, v36, v37
	v_cvt_pk_bf16_f32 v37, v42, v43
	global_store_dwordx4 v[50:51], v[34:37], off offset:256
	s_nop 1
	v_mov_b32_e32 v34, 1.0
	v_mov_b32_e32 v36, 1.0
	s_cbranch_vccnz .LBB0_576
	s_nop 0
	v_mov_b32_e32 v36, v172
	v_mov_b32_e32 v37, v173
	v_ffbh_u32_e32 v35, v37
	v_min_u32_e32 v35, 32, v35
	v_lshlrev_b64 v[36:37], v35, v[36:37]
	v_min_u32_e32 v36, 1, v36
	v_or_b32_e32 v36, v37, v36
	v_cvt_f32_u32_e32 v36, v36
	v_sub_u32_e32 v35, 32, v35
	v_ldexp_f32 v35, v36, v35
	v_fmamk_f32 v35, v35, 0x31000000, v232
	v_rsq_f32_e32 v36, v35
.LBB0_576:
	v_add_u32_e32 v35, 0xa0, v140
	v_mad_i64_i32 v[38:39], s[50:51], s10, v35, 0
	v_lshl_add_u64 v[38:39], v[38:39], 1, v[144:145]
	v_pk_mul_f32 v[32:33], v[32:33], v[36:37] op_sel_hi:[1,0]
	v_pk_mul_f32 v[30:31], v[30:31], v[36:37] op_sel_hi:[1,0]
	v_pk_mul_f32 v[40:41], v[28:29], v[36:37] op_sel_hi:[1,0]
	v_pk_mul_f32 v[28:29], v[26:27], v[36:37] op_sel_hi:[1,0]
	v_cvt_pk_bf16_f32 v26, v30, v31
	v_cvt_pk_bf16_f32 v27, v32, v33
	s_and_b64 vcc, exec, s[42:43]
	v_cvt_pk_bf16_f32 v28, v28, v29
	v_cvt_pk_bf16_f32 v29, v40, v41
	global_store_dwordx4 v[38:39], v[26:29], off
	v_pk_mul_f32 v[24:25], v[24:25], v[36:37] op_sel_hi:[1,0]
	v_pk_mul_f32 v[22:23], v[22:23], v[36:37] op_sel_hi:[1,0]
	v_pk_mul_f32 v[26:27], v[20:21], v[36:37] op_sel_hi:[1,0]
	v_pk_mul_f32 v[20:21], v[18:19], v[36:37] op_sel_hi:[1,0]
	v_cvt_pk_bf16_f32 v18, v22, v23
	v_cvt_pk_bf16_f32 v19, v24, v25
	s_nop 0
	v_cvt_pk_bf16_f32 v20, v20, v21
	v_cvt_pk_bf16_f32 v21, v26, v27
	global_store_dwordx4 v[38:39], v[18:21], off offset:256
	s_cbranch_vccnz .LBB0_578
	s_nop 0
	v_mov_b32_e32 v18, v174
	v_mov_b32_e32 v19, v175
	v_ffbh_u32_e32 v20, v19
	v_min_u32_e32 v20, 32, v20
	v_lshlrev_b64 v[18:19], v20, v[18:19]
	v_min_u32_e32 v18, 1, v18
	v_or_b32_e32 v18, v19, v18
	v_cvt_f32_u32_e32 v18, v18
	v_sub_u32_e32 v19, 32, v20
	v_ldexp_f32 v18, v18, v19
	v_fmamk_f32 v18, v18, 0x31000000, v232
	v_rsq_f32_e32 v34, v18
